# attention: the 4 workgroups of a (batch, head) take interleaved row pairs (2*qr + 8*round) instead of a quarter each, for L2 reuse of K/V rows across CUs of one XCD
# speedup vs baseline: 1.0092x; 1.0092x over previous
; #define LAS __attribute__((address_space(3)))
; __global__ void __launch_bounds__(NTHREADS, 2) mega(Args args) {
;     ...
;                 for (int it = vcu; it < BATCH * NH * 4; it += G) { const int qr = it & 3, h = (it >> 2) & 15, b = it >> 6;
;                     __syncthreads();
;                     { const int oc0 = (ML + b * CTX) >> 3;
;                       for (int ci = tid; ci < 4096; ci += NTHREADS) { const int o = ci >> 7, wq = ci & 127;
;                           const u32x4 kv = *(const u32x4*)(KTp + ((size_t)((oc0 + o) * NH + h)) * 1024 + wq * 8);
;                           *(LAS u32x4*)(lds + o * 2048 + (wq & ~15) * 16 + ((wq & 15) ^ (o & 2)) * 16) = kv;
;                           const u32x4 vv = *(const u32x4*)(VTp + ((size_t)((oc0 + o) * NH + h)) * 1024 + wq * 8);
;                           *(LAS u32x4*)(lds + 65536 + o * 2048 + wq * 16) = vv; }
;                       LAS float* rp = (LAS float*)(lds + LDS_MISC + 1024);
;                       for (int i = tid; i < 465; i += NTHREADS) rp[i] = rpg[h * 465 + i]; }
;                     __syncthreads();
; #pragma unroll 1
;                     for (int rd = 0; rd < 4; ++rd) attn_unit<true>(Qb, KTp, VTp, Ob, lds, b, h, 8 * qr + 2 * rd + (wave >> 2), wave & 3, 0, lane);
.LBB9_672:
	s_or_b64 exec, exec, s[50:51]
	s_and_b32 s5, s69, 3
	s_lshl_b32 s34, s5, 7
	s_lshl_b32 s5, s5, 1
	s_lshl_b32 s4, s4, 11
	s_add_i32 s50, s66, s5
	s_lshl_b32 s48, s72, 8
	v_add_u32_e32 v157, s4, v167
	s_or_b32 s4, s34, s4
	s_sub_i32 s51, s68, s5
	s_lshl_b32 s33, s72, 7
	v_lshl_add_u64 v[158:159], v[144:145], 0, s[48:49]
	v_lshl_add_u64 v[160:161], v[150:151], 0, s[48:49]
	v_add_u32_e32 v162, s4, v193
	s_mov_b32 s48, 0
	s_mov_b32 s52, s50
	s_mov_b32 s80, 8
	s_waitcnt lgkmcnt(0)
	s_barrier
	s_branch .LBB9_674
